# v032 stack + dead XB store removed in live last FFN-down epilogue + K-slice sample GEMM run before the prompt GEMM in both FFN-down phases
# speedup vs baseline: 1.0163x; 1.0163x over previous
; #define PG8_STAGE(bufoff, gbase, voff) do { _Pragma("unroll") for (int _i = 0; _i < 2; ++_i) \
;         __builtin_amdgcn_global_load_lds((const unsigned*)((const char*)(gbase) + (voff)[_i]), (PG8_LAS unsigned*)(lds + (bufoff) + ldsw + _i * 8192), 16, 0, 0); } while (0)
; #define PG8_BAR __builtin_amdgcn_s_barrier()
; template <class Epi, class Sched, bool ALIGN_EPI = false, bool SP2 = false>
; __device__ __forceinline__ void gemm_phase(PG8_LAS unsigned char* lds, const Gemm g, const Sched& S, const Epi& E) {
;     ...
;     const char* cA = (const char*)g.A + (size_t)cur.pm * tstep; const char* cB = (const char*)g.Bt + (size_t)cur.pn * tstep;
;     S.a_ready(cur);
;     if constexpr (SP2) {
;         PG8_STAGE(PG8_SB(0, 0), cB, voffB); PG8_STAGE(PG8_SB(0, 1), cB + hstep, voffB); PG8_STAGE(PG8_SA(0, 0), cA, voffA); PG8_STAGE(PG8_SA(0, 1), cA + hstep, voffA);
;         if (wr == 1) PG8_BAR;
; template <int L> __device__ __forceinline__ void common_gemms(const Args& a, LAS unsigned char* lds, int G, int bx, const XcdBarrier& xbar) {
;     ...
;             { pg8::Gemm g{ACT, W, MP, DM, DFF, 0}; pg8::StaticOrder S; S.init(MP, DM, G, bx);
;               EpiResid E{XR, XR + (size_t)MP * DM, XR, XB, SS + (L ? 4 : 2) * 32768};
;               pg8::gemm_phase<EpiResid, pg8::StaticOrder, true, true>(lds, g, S, E); }
.LBB0_1120:
	s_andn2_b64 vcc, exec, s[0:1]
	s_cbranch_vccnz .LBB0_1214
.LBB0_1121:
	s_branch .Lp7_r2
.Lp7_r1:
	s_lshr_b32 s1, s6, 6
	s_lshr_b32 s0, s6, 8
	s_lshl_b32 s52, s1, 10
	s_mul_i32 s5, s71, 0x160000
	s_mul_hi_i32 s4, s71, 0x160000
	s_add_u32 s48, s3, s5
	s_addc_u32 s49, s35, s4
	s_add_i32 s53, s52, 0
	s_add_i32 m0, s53, 0x10000
	s_mul_i32 s14, s72, 0x160000
	global_load_lds_dwordx4 v132, s[48:49]
	s_add_i32 m0, s53, 0x12000
	s_add_u32 s4, s48, 0xb0000
	global_load_lds_dwordx4 v136, s[48:49]
	s_addc_u32 s5, s49, 0
	s_add_i32 m0, s53, 0x14000
	s_mul_hi_i32 s7, s72, 0x160000
	global_load_lds_dwordx4 v132, s[4:5]
	s_add_i32 m0, s53, 0x16000
	s_add_u32 s44, s12, s14
	s_addc_u32 s45, s13, s7
	s_add_i32 s54, s53, 0x2000
	global_load_lds_dwordx4 v136, s[4:5]
	s_mov_b32 m0, s53
	s_add_u32 s4, s44, 0xb0000
	global_load_lds_dwordx4 v130, s[44:45]
	s_mov_b32 m0, s54
	s_addc_u32 s5, s45, 0
	s_add_i32 s55, s53, 0x4000
	global_load_lds_dwordx4 v134, s[44:45]
	s_mov_b32 m0, s55
	s_add_i32 s56, s53, 0x6000
	global_load_lds_dwordx4 v130, s[4:5]
	s_mov_b32 m0, s56
	v_mov_b32_e32 v139, 0
	global_load_lds_dwordx4 v134, s[4:5]
	s_waitcnt vmcnt(0)
	v_mov_b32_e32 v133, v139
	v_mov_b32_e32 v137, v139
	v_mov_b32_e32 v131, v139
	v_mov_b32_e32 v135, v139
	s_cmp_eq_u32 s0, 1
	s_mov_b32 s15, 0
	v_lshl_add_u64 v[8:9], s[48:49], 0, v[132:133]
	v_lshl_add_u64 v[6:7], s[48:49], 0, v[136:137]
	s_waitcnt lgkmcnt(0)
	v_lshl_add_u64 v[2:3], s[44:45], 0, v[130:131]
	s_cselect_b64 s[24:25], -1, 0
	s_cmp_lg_u32 s0, 1
	v_lshl_add_u64 v[4:5], s[44:45], 0, v[134:135]
	s_cbranch_scc1 .LBB0_1123
	s_barrier

; #define PG8_WAIT_V(n) asm volatile("s_waitcnt vmcnt(" #n ")" ::: "memory")
; #define PG8_BAR __builtin_amdgcn_s_barrier()
; template <class Epi, class Sched, bool ALIGN_EPI = false, bool SP2 = false>
; __device__ __forceinline__ void gemm_phase(PG8_LAS unsigned char* lds, const Gemm g, const Sched& S, const Epi& E) {
;     ...
;     PG8_WAIT_V(0);
;     if constexpr (!ALIGN_EPI) { if (wr == 0) PG8_BAR; }
;     PG8_BAR;
; template <int L> __device__ __forceinline__ void common_gemms(const Args& a, LAS unsigned char* lds, int G, int bx, const XcdBarrier& xbar) {
;     ...
;             { const int un = bx >> 3, sl = bx & 7, kb0 = (sl < 6) ? 3 * sl : 18 + 2 * (sl - 6), kbn = (sl < 6) ? 3 : 2;
.LBB0_1191:
	s_waitcnt vmcnt(0)
	s_barrier
	v_readlane_b32 s0, v253, 0
	v_readlane_b32 s1, v253, 1
	v_readlane_b32 s3, v253, 2
	v_readlane_b32 s38, v253, 3
	v_readlane_b32 s39, v253, 4
	v_readlane_b32 s40, v253, 5
	v_readlane_b32 s41, v253, 6
	v_readlane_b32 s43, v253, 7
	s_nop 4
	s_branch .Lp7_post
.Lp7_r2:
	s_and_b32 s4, s2, 7
	s_cmp_gt_u32 s4, 5
	s_cbranch_scc1 .LBB0_1215

; template <class Epi, class Sched, bool ALIGN_EPI = false, bool SP2 = false>
; __device__ __forceinline__ void gemm_phase(PG8_LAS unsigned char* lds, const Gemm g, const Sched& S, const Epi& E) {
;     const int tid = threadIdx.x, wid = __builtin_amdgcn_readfirstlane(tid >> 6), lane = tid & 63, wr = wid >> 2, wc = wid & 3, fr = lane & 15, fq = lane >> 4;
;     const int K = g.ld ? g.ld : g.K, nt = g.K / BK;
;     unsigned voffA[2], voffB[2];
; #pragma unroll
;     for (int i = 0; i < 2; ++i) { int R, C; stage_rc(tid * 16 + i * 8192, R, C); const int Rb = Epi::PERM ? ((R & ~31) + perm32(R & 31)) : R;
;         voffA[i] = (unsigned)(R * K + C) * 2u; voffB[i] = (unsigned)(Rb * K + C) * 2u; }
;     const size_t kstep = (size_t)(BK * 2);
;     const size_t hstep = (size_t)HALF * K * 2;
;     const size_t tstep = 2 * hstep;
;     const unsigned ldsw = (unsigned)wid * 1024u;
;     const int aoff = lds_byte(wr * 64 + fr, fq * 8), boff = lds_byte(wc * 32 + fr, fq * 8);
;     __device__ __forceinline__ void operator()(const pg8::f32x4 (&acc)[2][2][4][2], const pg8::Unit& u, int wr, int wc, int fr, int fq) const {
; #pragma unroll
;         for (int ai = 0; ai < 2; ++ai)
; #pragma unroll
;             for (int m = 0; m < 4; ++m) { float* rowp = part + (size_t)(ai * 128 + wr * 64 + m * 16 + fr) * 256 + wc * 32 + 8 * fq;
; #pragma unroll
;                 for (int bj = 0; bj < 2; ++bj) { *(f32x4*)(rowp + bj * 128) = acc[ai][bj][m][0]; *(f32x4*)(rowp + bj * 128 + 4) = acc[ai][bj][m][1]; } }
;     }
.LBB0_1200:
	s_add_u32 s0, s28, 0x25e00000
	s_addc_u32 s1, s29, 0
	s_ashr_i32 s3, s2, 31
	s_lshl_b64 s[4:5], s[2:3], 18
	v_mov_b32_e32 v131, 0
	s_add_u32 s4, s0, s4
	v_add_u32_e32 v130, 0xb0, v138
	v_add_u32_e32 v134, 0xa0, v138
	v_mov_b32_e32 v135, v131
	v_add_u32_e32 v136, 0x90, v138
	v_mov_b32_e32 v137, v131
	v_add_u32_e32 v140, 0x80, v138
	v_mov_b32_e32 v141, v131
	v_or_b32_e32 v142, 48, v138
	v_mov_b32_e32 v143, v131
	v_or_b32_e32 v144, 32, v138
	v_mov_b32_e32 v145, v131
	v_or_b32_e32 v146, 16, v138
	v_mov_b32_e32 v147, v131
	v_mov_b32_e32 v139, v131
	s_addc_u32 s5, s1, s5
	v_lshlrev_b64 v[132:133], 10, v[130:131]
	v_lshlrev_b64 v[134:135], 10, v[134:135]
	v_lshlrev_b64 v[136:137], 10, v[136:137]
	v_lshlrev_b64 v[140:141], 10, v[140:141]
	v_lshlrev_b64 v[142:143], 10, v[142:143]
	v_lshlrev_b64 v[144:145], 10, v[144:145]
	v_lshlrev_b64 v[146:147], 10, v[146:147]
	v_lshlrev_b64 v[138:139], 10, v[138:139]
	s_mov_b32 s7, 0
	v_lshl_add_u64 v[132:133], s[4:5], 0, v[132:133]
	s_lshl_b32 s6, s39, 2
	v_lshl_add_u64 v[134:135], s[4:5], 0, v[134:135]
	v_lshl_add_u64 v[136:137], s[4:5], 0, v[136:137]
	v_lshl_add_u64 v[140:141], s[4:5], 0, v[140:141]
	v_lshl_add_u64 v[142:143], s[4:5], 0, v[142:143]
	v_lshl_add_u64 v[144:145], s[4:5], 0, v[144:145]
	v_lshl_add_u64 v[146:147], s[4:5], 0, v[146:147]
	v_lshl_add_u64 v[138:139], s[4:5], 0, v[138:139]
	v_lshl_add_u64 v[132:133], v[132:133], 0, s[6:7]
	v_lshlrev_b32_e32 v130, 2, v156
	v_lshl_add_u64 v[134:135], v[134:135], 0, s[6:7]
	v_lshl_add_u64 v[136:137], v[136:137], 0, s[6:7]
	v_lshl_add_u64 v[140:141], v[140:141], 0, s[6:7]
	v_lshl_add_u64 v[142:143], v[142:143], 0, s[6:7]
	v_lshl_add_u64 v[144:145], v[144:145], 0, s[6:7]
	v_lshl_add_u64 v[146:147], v[146:147], 0, s[6:7]
	v_lshl_add_u64 v[138:139], v[138:139], 0, s[6:7]
	v_lshl_add_u64 v[132:133], v[132:133], 0, v[130:131]
	v_lshl_add_u64 v[134:135], v[134:135], 0, v[130:131]
	v_lshl_add_u64 v[136:137], v[136:137], 0, v[130:131]
	v_lshl_add_u64 v[140:141], v[140:141], 0, v[130:131]
	v_lshl_add_u64 v[142:143], v[142:143], 0, v[130:131]
	v_lshl_add_u64 v[144:145], v[144:145], 0, v[130:131]
	v_lshl_add_u64 v[146:147], v[146:147], 0, v[130:131]
	v_lshl_add_u64 v[130:131], v[138:139], 0, v[130:131]
	global_store_dwordx4 v[130:131], v[126:129], off
	global_store_dwordx4 v[130:131], v[122:125], off offset:16
	global_store_dwordx4 v[130:131], v[102:105], off offset:512
	global_store_dwordx4 v[130:131], v[94:97], off offset:528
	global_store_dwordx4 v[146:147], v[118:121], off
	global_store_dwordx4 v[146:147], v[114:117], off offset:16
	global_store_dwordx4 v[146:147], v[86:89], off offset:512
	global_store_dwordx4 v[146:147], v[82:85], off offset:528
	global_store_dwordx4 v[144:145], v[110:113], off
	global_store_dwordx4 v[144:145], v[106:109], off offset:16
	global_store_dwordx4 v[144:145], v[78:81], off offset:512
	global_store_dwordx4 v[144:145], v[74:77], off offset:528
	global_store_dwordx4 v[142:143], v[98:101], off
	global_store_dwordx4 v[142:143], v[90:93], off offset:16
	global_store_dwordx4 v[142:143], v[70:73], off offset:512
	global_store_dwordx4 v[142:143], v[66:69], off offset:528
	global_store_dwordx4 v[140:141], v[62:65], off
	global_store_dwordx4 v[140:141], v[58:61], off offset:16
	global_store_dwordx4 v[140:141], v[38:41], off offset:512
	global_store_dwordx4 v[140:141], v[30:33], off offset:528
	global_store_dwordx4 v[136:137], v[54:57], off
	global_store_dwordx4 v[136:137], v[50:53], off offset:16
	global_store_dwordx4 v[136:137], v[22:25], off offset:512
	global_store_dwordx4 v[136:137], v[18:21], off offset:528
	global_store_dwordx4 v[134:135], v[46:49], off
	global_store_dwordx4 v[134:135], v[42:45], off offset:16
	global_store_dwordx4 v[134:135], v[14:17], off offset:512
	global_store_dwordx4 v[134:135], v[10:13], off offset:528
	global_store_dwordx4 v[132:133], v[34:37], off
	global_store_dwordx4 v[132:133], v[26:29], off offset:16
	global_store_dwordx4 v[132:133], v[6:9], off offset:512
	global_store_dwordx4 v[132:133], v[2:5], off offset:528
	s_waitcnt vmcnt(0)
	s_barrier
	v_writelane_b32 v253, s0, 0
	v_writelane_b32 v253, s1, 1
	v_writelane_b32 v253, s3, 2
	v_writelane_b32 v253, s38, 3
	v_writelane_b32 v253, s39, 4
	v_writelane_b32 v253, s40, 5
	v_writelane_b32 v253, s41, 6
	v_writelane_b32 v253, s43, 7
	v_bfe_u32 v171, v0, 4, 2
	v_bfe_u32 v2, v0, 3, 25
	v_bfe_u32 v175, v0, 2, 4
	v_bfe_u32 v179, v0, 2, 2
	v_and_b32_e32 v182, 32, v0
	v_and_b32_e32 v172, 64, v0
	v_lshrrev_b32_e32 v180, 1, v0
	v_lshrrev_b32_e32 v181, 5, v0
	v_or_b32_e32 v178, 64, v2
	v_and_b32_e32 v170, 15, v0
	v_lshlrev_b32_e32 v173, 3, v171
	v_lshlrev_b32_e32 v174, 4, v171
	v_lshlrev_b32_e32 v176, 6, v0
	v_lshlrev_b32_e32 v177, 2, v0
	v_bitop3_b32 v159, v169, v182, 48 bitop3:0x6c
	v_or_b32_e32 v2, v159, v172
	v_and_b32_e32 v156, 24, v180
	v_and_b32_e32 v3, 4, v181
	v_and_or_b32 v4, v168, 48, v175
	v_lshrrev_b32_e32 v2, 1, v2
	v_or3_b32 v3, v3, v179, v156
	v_mul_u32_u24_e32 v160, 0xb00, v4
	v_and_or_b32 v5, v168, 32, v3
	v_or_b32_e32 v4, v2, v160
	s_add_u32 s3, s28, 0x2a00000
	v_lshlrev_b32_e32 v130, 1, v4
	v_mul_u32_u24_e32 v4, 0xb00, v5
	s_addc_u32 s35, s29, 0
	v_or_b32_e32 v4, v4, v2
	s_movk_i32 s0, 0x70
	s_add_u32 s8, s28, 0x9a00000
	v_lshlrev_b32_e32 v132, 1, v4
	v_and_or_b32 v4, v178, s0, v175
	s_movk_i32 s0, 0x60
	s_addc_u32 s9, s29, 0
	v_and_or_b32 v3, v178, s0, v3
	s_add_u32 s10, s28, 0x50000
	v_mul_u32_u24_e32 v161, 0xb00, v4
	v_mul_u32_u24_e32 v3, 0xb00, v3
	s_addc_u32 s11, s29, 0
	v_or_b32_e32 v4, v161, v2
	v_or_b32_e32 v2, v3, v2
	v_and_b32_e32 v158, 0x3c0, v176
	v_and_b32_e32 v157, 32, v177
	v_lshlrev_b32_e32 v134, 1, v4
	v_lshlrev_b32_e32 v136, 1, v2
	v_bitop3_b32 v162, v174, v157, v158 bitop3:0x36
	v_readfirstlane_b32 s6, v0
	s_nop 4
	s_branch .Lp7_r1
.Lp7_post:
	s_waitcnt vmcnt(0)
	v_cmp_eq_u32_e32 vcc, 0, v0
	s_waitcnt vmcnt(0)
	s_barrier
	s_and_saveexec_b64 s[4:5], vcc
	s_cbranch_execz .LBB0_1253
	v_mov_b32_e32 v2, s97
	s_waitcnt vmcnt(0) expcnt(0) lgkmcnt(0)
	ds_read_b32 v4, v2
	ds_read_b32 v2, v2 offset:4
	s_waitcnt lgkmcnt(1)
	v_cmp_ne_u32_e32 vcc, 0, v4
	s_cbranch_vccnz .LBB0_1221
	v_readlane_b32 s8, v252, 8
	v_readlane_b32 s9, v252, 9
	s_load_dwordx2 s[6:7], s[8:9], 0x4
	s_mov_b32 s35, 1
	v_mov_b32_e32 v18, 0
	s_waitcnt lgkmcnt(0)
	s_mul_i32 s6, s6, s7
	s_lshl_b32 s42, s6, 8
	s_add_u32 s6, s28, 0x1000
	s_addc_u32 s7, s29, 0
	s_add_u32 s8, s28, 0x1100
	s_addc_u32 s9, s29, 0
	s_add_u32 s10, s28, 0x1200
	s_addc_u32 s11, s29, 0
	s_add_u32 s14, s28, 0x1300
	s_addc_u32 s15, s29, 0
	s_branch .LBB0_1204

; #define PG8_STAGE(bufoff, gbase, voff) do { _Pragma("unroll") for (int _i = 0; _i < 2; ++_i) \
;         __builtin_amdgcn_global_load_lds((const unsigned*)((const char*)(gbase) + (voff)[_i]), (PG8_LAS unsigned*)(lds + (bufoff) + ldsw + _i * 8192), 16, 0, 0); } while (0)
; #define PG8_BAR __builtin_amdgcn_s_barrier()
; template <class Epi, class Sched, bool ALIGN_EPI = false, bool SP2 = false>
; __device__ __forceinline__ void gemm_phase(PG8_LAS unsigned char* lds, const Gemm g, const Sched& S, const Epi& E) {
;     ...
;     const char* cA = (const char*)g.A + (size_t)cur.pm * tstep; const char* cB = (const char*)g.Bt + (size_t)cur.pn * tstep;
;     S.a_ready(cur);
;     if constexpr (SP2) {
;         PG8_STAGE(PG8_SB(0, 0), cB, voffB); PG8_STAGE(PG8_SB(0, 1), cB + hstep, voffB); PG8_STAGE(PG8_SA(0, 0), cA, voffA); PG8_STAGE(PG8_SA(0, 1), cA + hstep, voffA);
;         if (wr == 1) PG8_BAR;
; template <int L> __device__ __forceinline__ void common_gemms(const Args& a, LAS unsigned char* lds, int G, int bx, const XcdBarrier& xbar) {
;     ...
;             { pg8::Gemm g{ACT, W, MP, DM, DFF, 0}; pg8::StaticOrder S; S.init(MP, DM, G, bx);
;               EpiResid E{XR, XR + (size_t)MP * DM, XR, XB, SS + (L ? 4 : 2) * 32768};
;               pg8::gemm_phase<EpiResid, pg8::StaticOrder, true, true>(lds, g, S, E); }
.LBB0_2069:
	s_andn2_b64 vcc, exec, s[0:1]
	s_cbranch_vccnz .LBB0_2163
.LBB0_2070:
	s_branch .Lp13_r2
.Lp13_r1:
	s_lshr_b32 s1, s6, 6
	s_lshr_b32 s0, s6, 8
	s_lshl_b32 s40, s1, 10
	s_mul_i32 s5, s57, 0x160000
	s_mul_hi_i32 s4, s57, 0x160000
	s_add_u32 s36, s3, s5
	s_addc_u32 s37, s35, s4
	s_add_i32 s41, s40, 0
	s_add_i32 m0, s41, 0x10000
	s_mul_i32 s14, s58, 0x160000
	global_load_lds_dwordx4 v132, s[36:37]
	s_add_i32 m0, s41, 0x12000
	s_add_u32 s4, s36, 0xb0000
	global_load_lds_dwordx4 v136, s[36:37]
	s_addc_u32 s5, s37, 0
	s_add_i32 m0, s41, 0x14000
	s_mul_hi_i32 s7, s58, 0x160000
	global_load_lds_dwordx4 v132, s[4:5]
	s_add_i32 m0, s41, 0x16000
	s_add_u32 s26, s12, s14
	s_addc_u32 s27, s13, s7
	s_add_i32 s42, s41, 0x2000
	global_load_lds_dwordx4 v136, s[4:5]
	s_mov_b32 m0, s41
	s_add_u32 s4, s26, 0xb0000
	global_load_lds_dwordx4 v130, s[26:27]
	s_mov_b32 m0, s42
	s_addc_u32 s5, s27, 0
	s_add_i32 s43, s41, 0x4000
	global_load_lds_dwordx4 v134, s[26:27]
	s_mov_b32 m0, s43
	s_add_i32 s44, s41, 0x6000
	global_load_lds_dwordx4 v130, s[4:5]
	s_mov_b32 m0, s44
	v_mov_b32_e32 v139, 0
	global_load_lds_dwordx4 v134, s[4:5]
	s_waitcnt vmcnt(0)
	v_mov_b32_e32 v133, v139
	v_mov_b32_e32 v137, v139
	v_mov_b32_e32 v131, v139
	v_mov_b32_e32 v135, v139
	s_cmp_eq_u32 s0, 1
	s_mov_b32 s15, 0
	v_lshl_add_u64 v[8:9], s[36:37], 0, v[132:133]
	v_lshl_add_u64 v[6:7], s[36:37], 0, v[136:137]
	s_waitcnt lgkmcnt(0)
	v_lshl_add_u64 v[2:3], s[26:27], 0, v[130:131]
	s_cselect_b64 s[18:19], -1, 0
	s_cmp_lg_u32 s0, 1
	v_lshl_add_u64 v[4:5], s[26:27], 0, v[134:135]
	s_cbranch_scc1 .LBB0_2072
	s_barrier

; __device__ __forceinline__ unsigned pk(float lo, float hi) { return pg8::cvt_pk_bf16(lo, hi); }
; __device__ __forceinline__ float dot4(f32x4 v) { return (v[0] * v[0] + v[1] * v[1]) + (v[2] * v[2] + v[3] * v[3]); }
;     __device__ __forceinline__ void operator()(const pg8::f32x4 (&acc)[2][2][4][2], const pg8::Unit& u, int wr, int wc, int fr, int fq) const {
;     ...
;             for (int m = 0; m < 4; ++m) {
;                 const int row = row0 + ai * 128 + m * 16;
;                 const float* xi = (row < MP) ? xin_p + (size_t)row * DM : xin_s + (size_t)(row - MP) * DM;
;                 float sq = 0.f;
; #pragma unroll
;                 for (int bj = 0; bj < 2; ++bj) { const int col = u.pn * 256 + bj * 128 + wc * 32 + 8 * fq;
;                     const f32x4 a0 = *(const f32x4*)(xi + col) + acc[ai][bj][m][0], a1 = *(const f32x4*)(xi + col + 4) + acc[ai][bj][m][1];
;                     *(f32x4*)(xout + (size_t)row * DM + col) = a0; *(f32x4*)(xout + (size_t)row * DM + col + 4) = a1;
;                     u32x4 w; w.x = pk(a0[0], a0[1]); w.y = pk(a0[2], a0[3]); w.z = pk(a1[0], a1[1]); w.w = pk(a1[2], a1[3]);
;                     *(u32x4*)(xb + (size_t)row * DM + col) = w;
;                     sq += dot4(a0) + dot4(a1); }
;                 sq += __shfl_xor(sq, 16); sq += __shfl_xor(sq, 32);
;                 if (fq == 0) atomicAdd(ssout + row, sq);
;             }
.LBB0_2089:
	v_lshl_add_u32 v152, s58, 8, v163
	v_cmp_lt_i32_e32 vcc, s50, v152
	s_and_saveexec_b64 s[26:27], vcc
	s_xor_b64 s[26:27], exec, s[26:27]
	v_add_u32_e32 v138, 0xffffc000, v152
	v_lshlrev_b64 v[148:149], 12, v[138:139]
	v_lshl_add_u64 v[154:155], s[8:9], 0, v[148:149]
	v_mov_b32_e32 v153, v139
	s_andn2_saveexec_b64 s[26:27], s[26:27]
	v_ashrrev_i32_e32 v153, 31, v152
	v_lshlrev_b64 v[148:149], 12, v[152:153]
	v_lshl_add_u64 v[154:155], s[16:17], 0, v[148:149]
	s_or_b64 exec, exec, s[26:27]
	v_lshl_or_b32 v148, s57, 8, v164
	v_ashrrev_i32_e32 v149, 31, v148
	v_lshlrev_b64 v[150:151], 2, v[148:149]
	v_lshl_add_u64 v[154:155], v[154:155], 0, v[150:151]
	global_load_dwordx4 v[166:169], v[154:155], off
	global_load_dwordx4 v[172:175], v[154:155], off offset:16
	v_lshlrev_b64 v[176:177], 12, v[152:153]
	v_lshlrev_b64 v[178:179], 11, v[152:153]
	v_lshl_add_u64 v[176:177], s[16:17], 0, v[176:177]
	v_lshl_add_u64 v[178:179], s[64:65], 0, v[178:179]
	v_lshl_add_u64 v[180:181], v[148:149], 1, v[178:179]
	v_lshl_add_u64 v[182:183], v[176:177], 0, v[150:151]
	v_xor_b32_e32 v138, 32, v165
	s_waitcnt vmcnt(0)
	v_pk_add_f32 v[128:129], v[128:129], v[168:169]
	v_pk_add_f32 v[126:127], v[126:127], v[166:167]
	v_pk_add_f32 v[168:169], v[124:125], v[174:175]
	v_pk_add_f32 v[166:167], v[122:123], v[172:173]
	global_store_dwordx4 v[182:183], v[126:129], off
	global_store_dwordx4 v[182:183], v[166:169], off offset:16
	v_cvt_pk_bf16_f32 v122, v126, v127
	v_cvt_pk_bf16_f32 v123, v128, v129
	v_cvt_pk_bf16_f32 v124, v166, v167
	v_cvt_pk_bf16_f32 v125, v168, v169
	s_nop 0
	global_load_dwordx4 v[172:175], v[154:155], off offset:512
	global_load_dwordx4 v[176:179], v[154:155], off offset:528
	v_mul_f32_e32 v124, v127, v127
	v_mul_f32_e32 v125, v129, v129
	v_mul_f32_e32 v127, v167, v167
	v_mul_f32_e32 v129, v169, v169
	v_fmac_f32_e32 v124, v126, v126
	v_fmac_f32_e32 v125, v128, v128
	v_fmac_f32_e32 v127, v166, v166
	v_fmac_f32_e32 v129, v168, v168
	v_add_f32_e32 v124, v124, v125
	v_add_f32_e32 v125, v127, v129
	v_add_f32_e32 v128, v124, v125
	v_and_b32_e32 v123, 64, v165
	v_xor_b32_e32 v122, 16, v165
	v_add_u32_e32 v123, 64, v123
	v_cmp_lt_i32_e32 vcc, v122, v123
	s_waitcnt vmcnt(1)
	v_pk_add_f32 v[120:121], v[120:121], v[174:175]
	v_pk_add_f32 v[118:119], v[118:119], v[172:173]
	s_waitcnt vmcnt(0)
	v_pk_add_f32 v[126:127], v[116:117], v[178:179]
	v_pk_add_f32 v[124:125], v[114:115], v[176:177]
	v_mul_f32_e32 v114, v119, v119
	v_mul_f32_e32 v115, v121, v121
	v_mul_f32_e32 v116, v125, v125
	v_mul_f32_e32 v117, v127, v127
	v_fmac_f32_e32 v114, v118, v118
	v_fmac_f32_e32 v115, v120, v120
	v_fmac_f32_e32 v116, v124, v124
	v_fmac_f32_e32 v117, v126, v126
	v_add_f32_e32 v114, v114, v115
	v_add_f32_e32 v115, v116, v117
	v_cndmask_b32_e32 v122, v165, v122, vcc
	v_add_f32_e32 v114, v114, v115
	v_lshlrev_b32_e32 v122, 2, v122
	v_add_f32_e32 v114, v128, v114
	ds_bpermute_b32 v115, v122, v114
	v_cmp_lt_i32_e32 vcc, v138, v123
	global_store_dwordx4 v[182:183], v[118:121], off offset:512
	global_store_dwordx4 v[182:183], v[124:127], off offset:528
	v_cndmask_b32_e32 v116, v165, v138, vcc
	v_cvt_pk_bf16_f32 v166, v118, v119
	s_waitcnt lgkmcnt(0)
	v_add_f32_e32 v114, v114, v115
	v_lshlrev_b32_e32 v118, 2, v116
	ds_bpermute_b32 v115, v118, v114
	v_cvt_pk_bf16_f32 v167, v120, v121
	v_cvt_pk_bf16_f32 v168, v124, v125
	v_cvt_pk_bf16_f32 v169, v126, v127
	s_nop 0
	s_and_saveexec_b64 s[26:27], s[0:1]
	s_cbranch_execz .LBB0_2095
	s_waitcnt lgkmcnt(0)
	v_add_f32_e32 v116, v114, v115
	v_lshl_add_u64 v[114:115], v[152:153], 2, s[10:11]
	global_atomic_add_f32 v[114:115], v116, off
.LBB0_2095:
	s_or_b64 exec, exec, s[26:27]
	s_waitcnt lgkmcnt(0)
	v_or_b32_e32 v114, 16, v152
	v_cmp_lt_i32_e32 vcc, s50, v114
	s_and_saveexec_b64 s[26:27], vcc
	s_xor_b64 s[26:27], exec, s[26:27]
	v_add_u32_e32 v138, 0xffffc010, v152
	v_lshlrev_b64 v[116:117], 12, v[138:139]
	v_lshl_add_u64 v[116:117], s[8:9], 0, v[116:117]
	v_mov_b32_e32 v115, v139
	s_andn2_saveexec_b64 s[26:27], s[26:27]
	v_ashrrev_i32_e32 v115, 31, v114
	v_lshlrev_b64 v[116:117], 12, v[114:115]
	v_lshl_add_u64 v[116:117], s[16:17], 0, v[116:117]
	s_or_b64 exec, exec, s[26:27]
	v_lshl_add_u64 v[116:117], v[116:117], 0, v[150:151]
	global_load_dwordx4 v[124:127], v[116:117], off
	global_load_dwordx4 v[166:169], v[116:117], off offset:16
	v_lshlrev_b64 v[120:121], 12, v[114:115]
	v_lshlrev_b64 v[128:129], 11, v[114:115]
	v_lshl_add_u64 v[120:121], s[16:17], 0, v[120:121]
	v_lshl_add_u64 v[128:129], s[64:65], 0, v[128:129]
	v_lshl_add_u64 v[120:121], v[120:121], 0, v[150:151]
	v_lshl_add_u64 v[128:129], v[148:149], 1, v[128:129]
	s_waitcnt vmcnt(1)
	v_pk_add_f32 v[112:113], v[112:113], v[126:127]
	v_pk_add_f32 v[110:111], v[110:111], v[124:125]
	s_waitcnt vmcnt(0)
	v_pk_add_f32 v[108:109], v[108:109], v[168:169]
	v_pk_add_f32 v[106:107], v[106:107], v[166:167]
	global_store_dwordx4 v[120:121], v[110:113], off
	global_store_dwordx4 v[120:121], v[106:109], off offset:16
	v_cvt_pk_bf16_f32 v124, v110, v111
	v_cvt_pk_bf16_f32 v125, v112, v113
	v_cvt_pk_bf16_f32 v126, v106, v107
	v_cvt_pk_bf16_f32 v127, v108, v109
	s_nop 0
	global_load_dwordx4 v[124:127], v[116:117], off offset:512
	s_nop 0
	global_load_dwordx4 v[166:169], v[116:117], off offset:528
	v_mul_f32_e32 v111, v111, v111
	v_mul_f32_e32 v113, v113, v113
	v_mul_f32_e32 v107, v107, v107
	v_mul_f32_e32 v109, v109, v109
	v_fmac_f32_e32 v111, v110, v110
	v_fmac_f32_e32 v113, v112, v112
	v_fmac_f32_e32 v107, v106, v106
	v_fmac_f32_e32 v109, v108, v108
	v_add_f32_e32 v106, v111, v113
	v_add_f32_e32 v107, v107, v109
	v_add_f32_e32 v110, v106, v107
	s_waitcnt vmcnt(1)
	v_pk_add_f32 v[104:105], v[104:105], v[126:127]
	v_pk_add_f32 v[102:103], v[102:103], v[124:125]
	s_waitcnt vmcnt(0)
	v_pk_add_f32 v[108:109], v[100:101], v[168:169]
	v_pk_add_f32 v[106:107], v[98:99], v[166:167]
	v_mul_f32_e32 v98, v103, v103
	v_mul_f32_e32 v99, v105, v105
	v_mul_f32_e32 v100, v107, v107
	v_mul_f32_e32 v101, v109, v109
	v_fmac_f32_e32 v98, v102, v102
	v_fmac_f32_e32 v99, v104, v104
	v_fmac_f32_e32 v100, v106, v106
	v_fmac_f32_e32 v101, v108, v108
	v_add_f32_e32 v98, v98, v99
	v_add_f32_e32 v99, v100, v101
	v_add_f32_e32 v98, v98, v99
	v_add_f32_e32 v98, v110, v98
	ds_bpermute_b32 v99, v122, v98
	global_store_dwordx4 v[120:121], v[102:105], off offset:512
	global_store_dwordx4 v[120:121], v[106:109], off offset:528
	v_cvt_pk_bf16_f32 v100, v102, v103
	v_cvt_pk_bf16_f32 v101, v104, v105
	s_waitcnt lgkmcnt(0)
	v_add_f32_e32 v98, v98, v99
	ds_bpermute_b32 v99, v118, v98
	v_cvt_pk_bf16_f32 v102, v106, v107
	v_cvt_pk_bf16_f32 v103, v108, v109
	s_nop 0
	s_and_saveexec_b64 s[26:27], s[0:1]
	s_cbranch_execz .LBB0_2101
	s_waitcnt lgkmcnt(0)
	v_add_f32_e32 v100, v98, v99
	v_lshl_add_u64 v[98:99], v[114:115], 2, s[10:11]
	global_atomic_add_f32 v[98:99], v100, off
; __device__ __forceinline__ unsigned pk(float lo, float hi) { return pg8::cvt_pk_bf16(lo, hi); }
; __device__ __forceinline__ float dot4(f32x4 v) { return (v[0] * v[0] + v[1] * v[1]) + (v[2] * v[2] + v[3] * v[3]); }
;     __device__ __forceinline__ void operator()(const pg8::f32x4 (&acc)[2][2][4][2], const pg8::Unit& u, int wr, int wc, int fr, int fq) const {
;     ...
;             for (int m = 0; m < 4; ++m) {
;                 const int row = row0 + ai * 128 + m * 16;
;                 const float* xi = (row < MP) ? xin_p + (size_t)row * DM : xin_s + (size_t)(row - MP) * DM;
;                 float sq = 0.f;
; #pragma unroll
;                 for (int bj = 0; bj < 2; ++bj) { const int col = u.pn * 256 + bj * 128 + wc * 32 + 8 * fq;
;                     const f32x4 a0 = *(const f32x4*)(xi + col) + acc[ai][bj][m][0], a1 = *(const f32x4*)(xi + col + 4) + acc[ai][bj][m][1];
;                     *(f32x4*)(xout + (size_t)row * DM + col) = a0; *(f32x4*)(xout + (size_t)row * DM + col + 4) = a1;
;                     u32x4 w; w.x = pk(a0[0], a0[1]); w.y = pk(a0[2], a0[3]); w.z = pk(a1[0], a1[1]); w.w = pk(a1[2], a1[3]);
;                     *(u32x4*)(xb + (size_t)row * DM + col) = w;
;                     sq += dot4(a0) + dot4(a1); }
;                 sq += __shfl_xor(sq, 16); sq += __shfl_xor(sq, 32);
;                 if (fq == 0) atomicAdd(ssout + row, sq);
;             }
.LBB0_2101:
	s_or_b64 exec, exec, s[26:27]
	s_waitcnt lgkmcnt(0)
	v_or_b32_e32 v98, 32, v152
	v_cmp_lt_i32_e32 vcc, s50, v98
	s_and_saveexec_b64 s[26:27], vcc
	s_xor_b64 s[26:27], exec, s[26:27]
	v_add_u32_e32 v138, 0xffffc020, v152
	v_lshlrev_b64 v[100:101], 12, v[138:139]
	v_lshl_add_u64 v[100:101], s[8:9], 0, v[100:101]
	v_mov_b32_e32 v99, v139
	s_andn2_saveexec_b64 s[26:27], s[26:27]
	v_ashrrev_i32_e32 v99, 31, v98
	v_lshlrev_b64 v[100:101], 12, v[98:99]
	v_lshl_add_u64 v[100:101], s[16:17], 0, v[100:101]
	s_or_b64 exec, exec, s[26:27]
	v_lshl_add_u64 v[108:109], v[100:101], 0, v[150:151]
	global_load_dwordx4 v[100:103], v[108:109], off
	global_load_dwordx4 v[104:107], v[108:109], off offset:16
	v_lshlrev_b64 v[110:111], 12, v[98:99]
	v_lshlrev_b64 v[112:113], 11, v[98:99]
	v_lshl_add_u64 v[110:111], s[16:17], 0, v[110:111]
	v_lshl_add_u64 v[112:113], s[64:65], 0, v[112:113]
	v_lshl_add_u64 v[110:111], v[110:111], 0, v[150:151]
	v_lshl_add_u64 v[112:113], v[148:149], 1, v[112:113]
	s_waitcnt vmcnt(1)
	v_pk_add_f32 v[96:97], v[96:97], v[102:103]
	v_pk_add_f32 v[94:95], v[94:95], v[100:101]
	s_waitcnt vmcnt(0)
	v_pk_add_f32 v[92:93], v[92:93], v[106:107]
	v_pk_add_f32 v[90:91], v[90:91], v[104:105]
	global_store_dwordx4 v[110:111], v[94:97], off
	global_store_dwordx4 v[110:111], v[90:93], off offset:16
	v_cvt_pk_bf16_f32 v100, v94, v95
	v_cvt_pk_bf16_f32 v101, v96, v97
	v_cvt_pk_bf16_f32 v102, v90, v91
	v_cvt_pk_bf16_f32 v103, v92, v93
	s_nop 0
	global_load_dwordx4 v[100:103], v[108:109], off offset:512
	s_nop 0
	global_load_dwordx4 v[104:107], v[108:109], off offset:528
	v_mul_f32_e32 v95, v95, v95
	v_mul_f32_e32 v97, v97, v97
	v_mul_f32_e32 v91, v91, v91
	v_mul_f32_e32 v93, v93, v93
	v_fmac_f32_e32 v95, v94, v94
	v_fmac_f32_e32 v97, v96, v96
	v_fmac_f32_e32 v91, v90, v90
	v_fmac_f32_e32 v93, v92, v92
	v_add_f32_e32 v90, v95, v97
	v_add_f32_e32 v91, v91, v93
	v_add_f32_e32 v94, v90, v91
	s_waitcnt vmcnt(1)
	v_pk_add_f32 v[88:89], v[88:89], v[102:103]
	v_pk_add_f32 v[86:87], v[86:87], v[100:101]
	s_waitcnt vmcnt(0)
	v_pk_add_f32 v[92:93], v[84:85], v[106:107]
	v_pk_add_f32 v[90:91], v[82:83], v[104:105]
	v_mul_f32_e32 v82, v87, v87
	v_mul_f32_e32 v83, v89, v89
	v_mul_f32_e32 v84, v91, v91
	v_mul_f32_e32 v85, v93, v93
	v_fmac_f32_e32 v82, v86, v86
	v_fmac_f32_e32 v83, v88, v88
	v_fmac_f32_e32 v84, v90, v90
	v_fmac_f32_e32 v85, v92, v92
	v_add_f32_e32 v82, v82, v83
	v_add_f32_e32 v83, v84, v85
	v_add_f32_e32 v82, v82, v83
	v_add_f32_e32 v82, v94, v82
	ds_bpermute_b32 v83, v122, v82
	global_store_dwordx4 v[110:111], v[86:89], off offset:512
	global_store_dwordx4 v[110:111], v[90:93], off offset:528
	v_cvt_pk_bf16_f32 v84, v86, v87
	v_cvt_pk_bf16_f32 v85, v88, v89
	s_waitcnt lgkmcnt(0)
	v_add_f32_e32 v82, v82, v83
	ds_bpermute_b32 v83, v118, v82
	v_cvt_pk_bf16_f32 v86, v90, v91
	v_cvt_pk_bf16_f32 v87, v92, v93
	s_nop 0
	s_and_saveexec_b64 s[26:27], s[0:1]
	s_cbranch_execz .LBB0_2107
	s_waitcnt lgkmcnt(0)
	v_add_f32_e32 v84, v82, v83
	v_lshl_add_u64 v[82:83], v[98:99], 2, s[10:11]
	global_atomic_add_f32 v[82:83], v84, off
.LBB0_2107:
	s_or_b64 exec, exec, s[26:27]
	s_waitcnt lgkmcnt(0)
	v_or_b32_e32 v82, 48, v152
	v_cmp_lt_i32_e32 vcc, s50, v82
	s_and_saveexec_b64 s[26:27], vcc
	s_xor_b64 s[26:27], exec, s[26:27]
	v_add_u32_e32 v138, 0xffffc030, v152
	v_lshlrev_b64 v[84:85], 12, v[138:139]
	v_lshl_add_u64 v[84:85], s[8:9], 0, v[84:85]
	v_mov_b32_e32 v83, v139
	s_andn2_saveexec_b64 s[26:27], s[26:27]
	v_ashrrev_i32_e32 v83, 31, v82
	v_lshlrev_b64 v[84:85], 12, v[82:83]
	v_lshl_add_u64 v[84:85], s[16:17], 0, v[84:85]
	s_or_b64 exec, exec, s[26:27]
	v_lshl_add_u64 v[92:93], v[84:85], 0, v[150:151]
	global_load_dwordx4 v[84:87], v[92:93], off
	global_load_dwordx4 v[88:91], v[92:93], off offset:16
	v_lshlrev_b64 v[94:95], 12, v[82:83]
	v_lshlrev_b64 v[96:97], 11, v[82:83]
	v_lshl_add_u64 v[94:95], s[16:17], 0, v[94:95]
	v_lshl_add_u64 v[96:97], s[64:65], 0, v[96:97]
	v_lshl_add_u64 v[94:95], v[94:95], 0, v[150:151]
	v_lshl_add_u64 v[96:97], v[148:149], 1, v[96:97]
	s_waitcnt vmcnt(1)
	v_pk_add_f32 v[80:81], v[80:81], v[86:87]
	v_pk_add_f32 v[78:79], v[78:79], v[84:85]
	s_waitcnt vmcnt(0)
	v_pk_add_f32 v[76:77], v[76:77], v[90:91]
	v_pk_add_f32 v[74:75], v[74:75], v[88:89]
	global_store_dwordx4 v[94:95], v[78:81], off
	global_store_dwordx4 v[94:95], v[74:77], off offset:16
	v_cvt_pk_bf16_f32 v84, v78, v79
	v_cvt_pk_bf16_f32 v85, v80, v81
	v_cvt_pk_bf16_f32 v86, v74, v75
	v_cvt_pk_bf16_f32 v87, v76, v77
	s_nop 0
	global_load_dwordx4 v[84:87], v[92:93], off offset:512
	s_nop 0
	global_load_dwordx4 v[88:91], v[92:93], off offset:528
	v_mul_f32_e32 v79, v79, v79
	v_mul_f32_e32 v81, v81, v81
	v_mul_f32_e32 v75, v75, v75
	v_mul_f32_e32 v77, v77, v77
	v_fmac_f32_e32 v79, v78, v78
	v_fmac_f32_e32 v81, v80, v80
	v_fmac_f32_e32 v75, v74, v74
	v_fmac_f32_e32 v77, v76, v76
	v_add_f32_e32 v74, v79, v81
	v_add_f32_e32 v75, v75, v77
	v_add_f32_e32 v78, v74, v75
	s_waitcnt vmcnt(1)
	v_pk_add_f32 v[72:73], v[72:73], v[86:87]
	v_pk_add_f32 v[70:71], v[70:71], v[84:85]
	s_waitcnt vmcnt(0)
	v_pk_add_f32 v[76:77], v[68:69], v[90:91]
	v_pk_add_f32 v[74:75], v[66:67], v[88:89]
	v_mul_f32_e32 v66, v71, v71
	v_mul_f32_e32 v67, v73, v73
	v_mul_f32_e32 v68, v75, v75
	v_mul_f32_e32 v69, v77, v77
	v_fmac_f32_e32 v66, v70, v70
	v_fmac_f32_e32 v67, v72, v72
	v_fmac_f32_e32 v68, v74, v74
	v_fmac_f32_e32 v69, v76, v76
	v_add_f32_e32 v66, v66, v67
	v_add_f32_e32 v67, v68, v69
	v_add_f32_e32 v66, v66, v67
	v_add_f32_e32 v66, v78, v66
	ds_bpermute_b32 v67, v122, v66
	global_store_dwordx4 v[94:95], v[70:73], off offset:512
	global_store_dwordx4 v[94:95], v[74:77], off offset:528
	v_cvt_pk_bf16_f32 v68, v70, v71
	v_cvt_pk_bf16_f32 v69, v72, v73
	s_waitcnt lgkmcnt(0)
	v_add_f32_e32 v66, v66, v67
	ds_bpermute_b32 v67, v118, v66
	v_cvt_pk_bf16_f32 v70, v74, v75
	v_cvt_pk_bf16_f32 v71, v76, v77
	s_nop 0
	s_and_saveexec_b64 s[26:27], s[0:1]
	s_cbranch_execz .LBB0_2113
	s_waitcnt lgkmcnt(0)
	v_add_f32_e32 v68, v66, v67
	v_lshl_add_u64 v[66:67], v[82:83], 2, s[10:11]
	global_atomic_add_f32 v[66:67], v68, off
; __device__ __forceinline__ unsigned pk(float lo, float hi) { return pg8::cvt_pk_bf16(lo, hi); }
; __device__ __forceinline__ float dot4(f32x4 v) { return (v[0] * v[0] + v[1] * v[1]) + (v[2] * v[2] + v[3] * v[3]); }
;     __device__ __forceinline__ void operator()(const pg8::f32x4 (&acc)[2][2][4][2], const pg8::Unit& u, int wr, int wc, int fr, int fq) const {
;     ...
;             for (int m = 0; m < 4; ++m) {
;                 const int row = row0 + ai * 128 + m * 16;
;                 const float* xi = (row < MP) ? xin_p + (size_t)row * DM : xin_s + (size_t)(row - MP) * DM;
;                 float sq = 0.f;
; #pragma unroll
;                 for (int bj = 0; bj < 2; ++bj) { const int col = u.pn * 256 + bj * 128 + wc * 32 + 8 * fq;
;                     const f32x4 a0 = *(const f32x4*)(xi + col) + acc[ai][bj][m][0], a1 = *(const f32x4*)(xi + col + 4) + acc[ai][bj][m][1];
;                     *(f32x4*)(xout + (size_t)row * DM + col) = a0; *(f32x4*)(xout + (size_t)row * DM + col + 4) = a1;
;                     u32x4 w; w.x = pk(a0[0], a0[1]); w.y = pk(a0[2], a0[3]); w.z = pk(a1[0], a1[1]); w.w = pk(a1[2], a1[3]);
;                     *(u32x4*)(xb + (size_t)row * DM + col) = w;
;                     sq += dot4(a0) + dot4(a1); }
;                 sq += __shfl_xor(sq, 16); sq += __shfl_xor(sq, 32);
;                 if (fq == 0) atomicAdd(ssout + row, sq);
;             }
.LBB0_2113:
	s_or_b64 exec, exec, s[26:27]
	s_waitcnt lgkmcnt(0)
	v_add_u32_e32 v66, 0x80, v152
	v_cmp_lt_i32_e32 vcc, s51, v152
	s_and_saveexec_b64 s[26:27], vcc
	s_xor_b64 s[26:27], exec, s[26:27]
	v_add_u32_e32 v138, 0xffffc080, v152
	v_lshlrev_b64 v[68:69], 12, v[138:139]
	v_lshl_add_u64 v[68:69], s[8:9], 0, v[68:69]
	v_mov_b32_e32 v67, v139
	s_andn2_saveexec_b64 s[26:27], s[26:27]
	v_ashrrev_i32_e32 v67, 31, v66
	v_lshlrev_b64 v[68:69], 12, v[66:67]
	v_lshl_add_u64 v[68:69], s[16:17], 0, v[68:69]
	s_or_b64 exec, exec, s[26:27]
	v_lshl_add_u64 v[76:77], v[68:69], 0, v[150:151]
	global_load_dwordx4 v[68:71], v[76:77], off
	global_load_dwordx4 v[72:75], v[76:77], off offset:16
	v_lshlrev_b64 v[78:79], 12, v[66:67]
	v_lshlrev_b64 v[80:81], 11, v[66:67]
	v_lshl_add_u64 v[78:79], s[16:17], 0, v[78:79]
	v_lshl_add_u64 v[80:81], s[64:65], 0, v[80:81]
	v_lshl_add_u64 v[78:79], v[78:79], 0, v[150:151]
	v_lshl_add_u64 v[80:81], v[148:149], 1, v[80:81]
	s_waitcnt vmcnt(1)
	v_pk_add_f32 v[64:65], v[64:65], v[70:71]
	v_pk_add_f32 v[62:63], v[62:63], v[68:69]
	s_waitcnt vmcnt(0)
	v_pk_add_f32 v[60:61], v[60:61], v[74:75]
	v_pk_add_f32 v[58:59], v[58:59], v[72:73]
	global_store_dwordx4 v[78:79], v[62:65], off
	global_store_dwordx4 v[78:79], v[58:61], off offset:16
	v_cvt_pk_bf16_f32 v68, v62, v63
	v_cvt_pk_bf16_f32 v69, v64, v65
	v_cvt_pk_bf16_f32 v70, v58, v59
	v_cvt_pk_bf16_f32 v71, v60, v61
	s_nop 0
	global_load_dwordx4 v[68:71], v[76:77], off offset:512
	s_nop 0
	global_load_dwordx4 v[72:75], v[76:77], off offset:528
	v_mul_f32_e32 v63, v63, v63
	v_mul_f32_e32 v65, v65, v65
	v_mul_f32_e32 v59, v59, v59
	v_mul_f32_e32 v61, v61, v61
	v_fmac_f32_e32 v63, v62, v62
	v_fmac_f32_e32 v65, v64, v64
	v_fmac_f32_e32 v59, v58, v58
	v_fmac_f32_e32 v61, v60, v60
	v_add_f32_e32 v58, v63, v65
	v_add_f32_e32 v59, v59, v61
	v_add_f32_e32 v62, v58, v59
	s_waitcnt vmcnt(1)
	v_pk_add_f32 v[56:57], v[56:57], v[70:71]
	v_pk_add_f32 v[54:55], v[54:55], v[68:69]
	s_waitcnt vmcnt(0)
	v_pk_add_f32 v[60:61], v[52:53], v[74:75]
	v_pk_add_f32 v[58:59], v[50:51], v[72:73]
	v_mul_f32_e32 v50, v55, v55
	v_mul_f32_e32 v51, v57, v57
	v_mul_f32_e32 v52, v59, v59
	v_mul_f32_e32 v53, v61, v61
	v_fmac_f32_e32 v50, v54, v54
	v_fmac_f32_e32 v51, v56, v56
	v_fmac_f32_e32 v52, v58, v58
	v_fmac_f32_e32 v53, v60, v60
	v_add_f32_e32 v50, v50, v51
	v_add_f32_e32 v51, v52, v53
	v_add_f32_e32 v50, v50, v51
	v_add_f32_e32 v50, v62, v50
	ds_bpermute_b32 v51, v122, v50
	global_store_dwordx4 v[78:79], v[54:57], off offset:512
	global_store_dwordx4 v[78:79], v[58:61], off offset:528
	v_cvt_pk_bf16_f32 v52, v54, v55
	v_cvt_pk_bf16_f32 v53, v56, v57
	s_waitcnt lgkmcnt(0)
	v_add_f32_e32 v50, v50, v51
	ds_bpermute_b32 v51, v118, v50
	v_cvt_pk_bf16_f32 v54, v58, v59
	v_cvt_pk_bf16_f32 v55, v60, v61
	s_nop 0
	s_and_saveexec_b64 s[26:27], s[0:1]
	s_cbranch_execz .LBB0_2119
	s_waitcnt lgkmcnt(0)
	v_add_f32_e32 v52, v50, v51
	v_lshl_add_u64 v[50:51], v[66:67], 2, s[10:11]
	global_atomic_add_f32 v[50:51], v52, off
.LBB0_2119:
	s_or_b64 exec, exec, s[26:27]
	s_waitcnt lgkmcnt(0)
	v_add_u32_e32 v50, 0x90, v152
	v_cmp_lt_i32_e32 vcc, s52, v152
	s_and_saveexec_b64 s[26:27], vcc
	s_xor_b64 s[26:27], exec, s[26:27]
	v_add_u32_e32 v138, 0xffffc090, v152
	v_lshlrev_b64 v[52:53], 12, v[138:139]
	v_lshl_add_u64 v[52:53], s[8:9], 0, v[52:53]
	v_mov_b32_e32 v51, v139
	s_andn2_saveexec_b64 s[26:27], s[26:27]
	v_ashrrev_i32_e32 v51, 31, v50
	v_lshlrev_b64 v[52:53], 12, v[50:51]
	v_lshl_add_u64 v[52:53], s[16:17], 0, v[52:53]
	s_or_b64 exec, exec, s[26:27]
	v_lshl_add_u64 v[60:61], v[52:53], 0, v[150:151]
	global_load_dwordx4 v[52:55], v[60:61], off
	global_load_dwordx4 v[56:59], v[60:61], off offset:16
	v_lshlrev_b64 v[62:63], 12, v[50:51]
	v_lshlrev_b64 v[64:65], 11, v[50:51]
	v_lshl_add_u64 v[62:63], s[16:17], 0, v[62:63]
	v_lshl_add_u64 v[64:65], s[64:65], 0, v[64:65]
	v_lshl_add_u64 v[62:63], v[62:63], 0, v[150:151]
	v_lshl_add_u64 v[64:65], v[148:149], 1, v[64:65]
	s_waitcnt vmcnt(1)
	v_pk_add_f32 v[48:49], v[48:49], v[54:55]
	v_pk_add_f32 v[46:47], v[46:47], v[52:53]
	s_waitcnt vmcnt(0)
	v_pk_add_f32 v[44:45], v[44:45], v[58:59]
	v_pk_add_f32 v[42:43], v[42:43], v[56:57]
	global_store_dwordx4 v[62:63], v[46:49], off
	global_store_dwordx4 v[62:63], v[42:45], off offset:16
	v_cvt_pk_bf16_f32 v52, v46, v47
	v_cvt_pk_bf16_f32 v53, v48, v49
	v_cvt_pk_bf16_f32 v54, v42, v43
	v_cvt_pk_bf16_f32 v55, v44, v45
	s_nop 0
	global_load_dwordx4 v[52:55], v[60:61], off offset:512
	s_nop 0
	global_load_dwordx4 v[56:59], v[60:61], off offset:528
	v_mul_f32_e32 v47, v47, v47
	v_mul_f32_e32 v49, v49, v49
	v_mul_f32_e32 v43, v43, v43
	v_mul_f32_e32 v45, v45, v45
	v_fmac_f32_e32 v47, v46, v46
	v_fmac_f32_e32 v49, v48, v48
	v_fmac_f32_e32 v43, v42, v42
	v_fmac_f32_e32 v45, v44, v44
	v_add_f32_e32 v42, v47, v49
	v_add_f32_e32 v43, v43, v45
	v_add_f32_e32 v46, v42, v43
	s_waitcnt vmcnt(1)
	v_pk_add_f32 v[40:41], v[40:41], v[54:55]
	v_pk_add_f32 v[38:39], v[38:39], v[52:53]
	s_waitcnt vmcnt(0)
	v_pk_add_f32 v[44:45], v[36:37], v[58:59]
	v_pk_add_f32 v[42:43], v[34:35], v[56:57]
	v_mul_f32_e32 v34, v39, v39
	v_mul_f32_e32 v35, v41, v41
	v_mul_f32_e32 v36, v43, v43
	v_mul_f32_e32 v37, v45, v45
	v_fmac_f32_e32 v34, v38, v38
	v_fmac_f32_e32 v35, v40, v40
	v_fmac_f32_e32 v36, v42, v42
	v_fmac_f32_e32 v37, v44, v44
	v_add_f32_e32 v34, v34, v35
	v_add_f32_e32 v35, v36, v37
	v_add_f32_e32 v34, v34, v35
	v_add_f32_e32 v34, v46, v34
	ds_bpermute_b32 v35, v122, v34
	global_store_dwordx4 v[62:63], v[38:41], off offset:512
	global_store_dwordx4 v[62:63], v[42:45], off offset:528
	v_cvt_pk_bf16_f32 v36, v38, v39
	v_cvt_pk_bf16_f32 v37, v40, v41
	s_waitcnt lgkmcnt(0)
	v_add_f32_e32 v34, v34, v35
	ds_bpermute_b32 v35, v118, v34
	v_cvt_pk_bf16_f32 v38, v42, v43
	v_cvt_pk_bf16_f32 v39, v44, v45
	s_nop 0
	s_and_saveexec_b64 s[26:27], s[0:1]
	s_cbranch_execz .LBB0_2125
	s_waitcnt lgkmcnt(0)
	v_add_f32_e32 v36, v34, v35
	v_lshl_add_u64 v[34:35], v[50:51], 2, s[10:11]
	global_atomic_add_f32 v[34:35], v36, off
; __device__ __forceinline__ unsigned pk(float lo, float hi) { return pg8::cvt_pk_bf16(lo, hi); }
; __device__ __forceinline__ float dot4(f32x4 v) { return (v[0] * v[0] + v[1] * v[1]) + (v[2] * v[2] + v[3] * v[3]); }
;     __device__ __forceinline__ void operator()(const pg8::f32x4 (&acc)[2][2][4][2], const pg8::Unit& u, int wr, int wc, int fr, int fq) const {
;     ...
;             for (int m = 0; m < 4; ++m) {
;                 const int row = row0 + ai * 128 + m * 16;
;                 const float* xi = (row < MP) ? xin_p + (size_t)row * DM : xin_s + (size_t)(row - MP) * DM;
;                 float sq = 0.f;
; #pragma unroll
;                 for (int bj = 0; bj < 2; ++bj) { const int col = u.pn * 256 + bj * 128 + wc * 32 + 8 * fq;
;                     const f32x4 a0 = *(const f32x4*)(xi + col) + acc[ai][bj][m][0], a1 = *(const f32x4*)(xi + col + 4) + acc[ai][bj][m][1];
;                     *(f32x4*)(xout + (size_t)row * DM + col) = a0; *(f32x4*)(xout + (size_t)row * DM + col + 4) = a1;
;                     u32x4 w; w.x = pk(a0[0], a0[1]); w.y = pk(a0[2], a0[3]); w.z = pk(a1[0], a1[1]); w.w = pk(a1[2], a1[3]);
;                     *(u32x4*)(xb + (size_t)row * DM + col) = w;
;                     sq += dot4(a0) + dot4(a1); }
;                 sq += __shfl_xor(sq, 16); sq += __shfl_xor(sq, 32);
;                 if (fq == 0) atomicAdd(ssout + row, sq);
;             }
.LBB0_2125:
	s_or_b64 exec, exec, s[26:27]
	s_waitcnt lgkmcnt(0)
	v_add_u32_e32 v34, 0xa0, v152
	v_cmp_lt_i32_e32 vcc, s53, v152
	s_and_saveexec_b64 s[26:27], vcc
	s_xor_b64 s[26:27], exec, s[26:27]
	v_add_u32_e32 v138, 0xffffc0a0, v152
	v_lshlrev_b64 v[36:37], 12, v[138:139]
	v_lshl_add_u64 v[36:37], s[8:9], 0, v[36:37]
	v_mov_b32_e32 v35, v139
	s_andn2_saveexec_b64 s[26:27], s[26:27]
	v_ashrrev_i32_e32 v35, 31, v34
	v_lshlrev_b64 v[36:37], 12, v[34:35]
	v_lshl_add_u64 v[36:37], s[16:17], 0, v[36:37]
	s_or_b64 exec, exec, s[26:27]
	v_lshl_add_u64 v[44:45], v[36:37], 0, v[150:151]
	global_load_dwordx4 v[36:39], v[44:45], off
	global_load_dwordx4 v[40:43], v[44:45], off offset:16
	v_lshlrev_b64 v[46:47], 12, v[34:35]
	v_lshlrev_b64 v[48:49], 11, v[34:35]
	v_lshl_add_u64 v[46:47], s[16:17], 0, v[46:47]
	v_lshl_add_u64 v[48:49], s[64:65], 0, v[48:49]
	v_lshl_add_u64 v[46:47], v[46:47], 0, v[150:151]
	v_lshl_add_u64 v[48:49], v[148:149], 1, v[48:49]
	s_waitcnt vmcnt(1)
	v_pk_add_f32 v[32:33], v[32:33], v[38:39]
	v_pk_add_f32 v[30:31], v[30:31], v[36:37]
	s_waitcnt vmcnt(0)
	v_pk_add_f32 v[28:29], v[28:29], v[42:43]
	v_pk_add_f32 v[26:27], v[26:27], v[40:41]
	global_store_dwordx4 v[46:47], v[30:33], off
	global_store_dwordx4 v[46:47], v[26:29], off offset:16
	v_cvt_pk_bf16_f32 v36, v30, v31
	v_cvt_pk_bf16_f32 v37, v32, v33
	v_cvt_pk_bf16_f32 v38, v26, v27
	v_cvt_pk_bf16_f32 v39, v28, v29
	s_nop 0
	global_load_dwordx4 v[36:39], v[44:45], off offset:512
	s_nop 0
	global_load_dwordx4 v[40:43], v[44:45], off offset:528
	v_mul_f32_e32 v31, v31, v31
	v_mul_f32_e32 v33, v33, v33
	v_mul_f32_e32 v27, v27, v27
	v_mul_f32_e32 v29, v29, v29
	v_fmac_f32_e32 v31, v30, v30
	v_fmac_f32_e32 v33, v32, v32
	v_fmac_f32_e32 v27, v26, v26
	v_fmac_f32_e32 v29, v28, v28
	v_add_f32_e32 v26, v31, v33
	v_add_f32_e32 v27, v27, v29
	v_add_f32_e32 v30, v26, v27
	s_waitcnt vmcnt(1)
	v_pk_add_f32 v[24:25], v[24:25], v[38:39]
	v_pk_add_f32 v[22:23], v[22:23], v[36:37]
	s_waitcnt vmcnt(0)
	v_pk_add_f32 v[28:29], v[20:21], v[42:43]
	v_pk_add_f32 v[26:27], v[18:19], v[40:41]
	v_mul_f32_e32 v18, v23, v23
	v_mul_f32_e32 v19, v25, v25
	v_mul_f32_e32 v20, v27, v27
	v_mul_f32_e32 v21, v29, v29
	v_fmac_f32_e32 v18, v22, v22
	v_fmac_f32_e32 v19, v24, v24
	v_fmac_f32_e32 v20, v26, v26
	v_fmac_f32_e32 v21, v28, v28
	v_add_f32_e32 v18, v18, v19
	v_add_f32_e32 v19, v20, v21
	v_add_f32_e32 v18, v18, v19
	v_add_f32_e32 v18, v30, v18
	ds_bpermute_b32 v19, v122, v18
	global_store_dwordx4 v[46:47], v[22:25], off offset:512
	global_store_dwordx4 v[46:47], v[26:29], off offset:528
	v_cvt_pk_bf16_f32 v20, v22, v23
	v_cvt_pk_bf16_f32 v21, v24, v25
	s_waitcnt lgkmcnt(0)
	v_add_f32_e32 v18, v18, v19
	ds_bpermute_b32 v19, v118, v18
	v_cvt_pk_bf16_f32 v22, v26, v27
	v_cvt_pk_bf16_f32 v23, v28, v29
	s_nop 0
	s_and_saveexec_b64 s[26:27], s[0:1]
	s_cbranch_execz .LBB0_2131
	s_waitcnt lgkmcnt(0)
	v_add_f32_e32 v20, v18, v19
	v_lshl_add_u64 v[18:19], v[34:35], 2, s[10:11]
	global_atomic_add_f32 v[18:19], v20, off
.LBB0_2131:
	s_or_b64 exec, exec, s[26:27]
	s_waitcnt lgkmcnt(0)
	v_add_u32_e32 v18, 0xb0, v152
	v_cmp_lt_i32_e32 vcc, s54, v152
	s_and_saveexec_b64 s[26:27], vcc
	s_xor_b64 s[26:27], exec, s[26:27]
	v_add_u32_e32 v138, 0xffffc0b0, v152
	v_lshlrev_b64 v[20:21], 12, v[138:139]
	v_lshl_add_u64 v[20:21], s[8:9], 0, v[20:21]
	v_mov_b32_e32 v19, v139
	s_andn2_saveexec_b64 s[26:27], s[26:27]
	v_ashrrev_i32_e32 v19, 31, v18
	v_lshlrev_b64 v[20:21], 12, v[18:19]
	v_lshl_add_u64 v[20:21], s[16:17], 0, v[20:21]
	s_or_b64 exec, exec, s[26:27]
	v_lshl_add_u64 v[28:29], v[20:21], 0, v[150:151]
	global_load_dwordx4 v[20:23], v[28:29], off
	global_load_dwordx4 v[24:27], v[28:29], off offset:16
	v_lshlrev_b64 v[30:31], 12, v[18:19]
	v_lshlrev_b64 v[32:33], 11, v[18:19]
	v_lshl_add_u64 v[30:31], s[16:17], 0, v[30:31]
	v_lshl_add_u64 v[32:33], s[64:65], 0, v[32:33]
	v_lshl_add_u64 v[30:31], v[30:31], 0, v[150:151]
	v_lshl_add_u64 v[32:33], v[148:149], 1, v[32:33]
	s_waitcnt vmcnt(1)
	v_pk_add_f32 v[16:17], v[16:17], v[22:23]
	v_pk_add_f32 v[14:15], v[14:15], v[20:21]
	s_waitcnt vmcnt(0)
	v_pk_add_f32 v[12:13], v[12:13], v[26:27]
	v_pk_add_f32 v[10:11], v[10:11], v[24:25]
	global_store_dwordx4 v[30:31], v[14:17], off
	global_store_dwordx4 v[30:31], v[10:13], off offset:16
	v_cvt_pk_bf16_f32 v20, v14, v15
	v_cvt_pk_bf16_f32 v21, v16, v17
	v_cvt_pk_bf16_f32 v22, v10, v11
	v_cvt_pk_bf16_f32 v23, v12, v13
	s_nop 0
	global_load_dwordx4 v[20:23], v[28:29], off offset:512
	s_nop 0
	global_load_dwordx4 v[24:27], v[28:29], off offset:528
	v_mul_f32_e32 v15, v15, v15
	v_mul_f32_e32 v17, v17, v17
	v_mul_f32_e32 v11, v11, v11
	v_mul_f32_e32 v13, v13, v13
	v_fmac_f32_e32 v15, v14, v14
	v_fmac_f32_e32 v17, v16, v16
	v_fmac_f32_e32 v11, v10, v10
	v_fmac_f32_e32 v13, v12, v12
	v_add_f32_e32 v10, v15, v17
	v_add_f32_e32 v11, v11, v13
	v_add_f32_e32 v14, v10, v11
	s_waitcnt vmcnt(1)
	v_pk_add_f32 v[8:9], v[8:9], v[22:23]
	v_pk_add_f32 v[6:7], v[6:7], v[20:21]
	s_waitcnt vmcnt(0)
	v_pk_add_f32 v[12:13], v[4:5], v[26:27]
	v_pk_add_f32 v[10:11], v[2:3], v[24:25]
	v_mul_f32_e32 v2, v7, v7
	v_mul_f32_e32 v3, v9, v9
	v_mul_f32_e32 v4, v11, v11
	v_mul_f32_e32 v5, v13, v13
	v_fmac_f32_e32 v2, v6, v6
	v_fmac_f32_e32 v3, v8, v8
	v_fmac_f32_e32 v4, v10, v10
	v_fmac_f32_e32 v5, v12, v12
	v_add_f32_e32 v2, v2, v3
	v_add_f32_e32 v3, v4, v5
	v_add_f32_e32 v2, v2, v3
	v_add_f32_e32 v2, v14, v2
	ds_bpermute_b32 v3, v122, v2
	global_store_dwordx4 v[30:31], v[6:9], off offset:512
	global_store_dwordx4 v[30:31], v[10:13], off offset:528
	v_cvt_pk_bf16_f32 v4, v6, v7
	v_cvt_pk_bf16_f32 v5, v8, v9
	s_waitcnt lgkmcnt(0)
	v_add_f32_e32 v2, v2, v3
	ds_bpermute_b32 v3, v118, v2
	v_cvt_pk_bf16_f32 v6, v10, v11
	v_cvt_pk_bf16_f32 v7, v12, v13
	s_nop 0
	s_and_saveexec_b64 s[26:27], s[0:1]
	s_cbranch_execz .LBB0_2137
	s_waitcnt lgkmcnt(0)
	v_add_f32_e32 v4, v2, v3
	v_lshl_add_u64 v[2:3], v[18:19], 2, s[10:11]
	global_atomic_add_f32 v[2:3], v4, off

; #define PG8_WAIT_V(n) asm volatile("s_waitcnt vmcnt(" #n ")" ::: "memory")
; #define PG8_BAR __builtin_amdgcn_s_barrier()
; template <class Epi, class Sched, bool ALIGN_EPI = false, bool SP2 = false>
; __device__ __forceinline__ void gemm_phase(PG8_LAS unsigned char* lds, const Gemm g, const Sched& S, const Epi& E) {
;     ...
;     PG8_WAIT_V(0);
;     if constexpr (!ALIGN_EPI) { if (wr == 0) PG8_BAR; }
;     PG8_BAR;
; template <int L> __device__ __forceinline__ void common_gemms(const Args& a, LAS unsigned char* lds, int G, int bx, const XcdBarrier& xbar) {
;     ...
;             { const int un = bx >> 3, sl = bx & 7, kb0 = (sl < 6) ? 3 * sl : 18 + 2 * (sl - 6), kbn = (sl < 6) ? 3 : 2;
.LBB0_2140:
	s_waitcnt vmcnt(0)
	s_barrier
	v_readlane_b32 s0, v253, 8
	v_readlane_b32 s1, v253, 9
	v_readlane_b32 s3, v253, 10
	v_readlane_b32 s18, v253, 11
	v_readlane_b32 s19, v253, 12
	v_readlane_b32 s20, v253, 13
	v_readlane_b32 s21, v253, 14
	v_readlane_b32 s23, v253, 15
	s_nop 4
	s_branch .Lp13_post

; template <class Epi, class Sched, bool ALIGN_EPI = false, bool SP2 = false>
; __device__ __forceinline__ void gemm_phase(PG8_LAS unsigned char* lds, const Gemm g, const Sched& S, const Epi& E) {
;     const int tid = threadIdx.x, wid = __builtin_amdgcn_readfirstlane(tid >> 6), lane = tid & 63, wr = wid >> 2, wc = wid & 3, fr = lane & 15, fq = lane >> 4;
;     const int K = g.ld ? g.ld : g.K, nt = g.K / BK;
;     unsigned voffA[2], voffB[2];
; #pragma unroll
;     for (int i = 0; i < 2; ++i) { int R, C; stage_rc(tid * 16 + i * 8192, R, C); const int Rb = Epi::PERM ? ((R & ~31) + perm32(R & 31)) : R;
;         voffA[i] = (unsigned)(R * K + C) * 2u; voffB[i] = (unsigned)(Rb * K + C) * 2u; }
;     const size_t kstep = (size_t)(BK * 2);
;     const size_t hstep = (size_t)HALF * K * 2;
;     const size_t tstep = 2 * hstep;
;     const unsigned ldsw = (unsigned)wid * 1024u;
;     const int aoff = lds_byte(wr * 64 + fr, fq * 8), boff = lds_byte(wc * 32 + fr, fq * 8);
;     __device__ __forceinline__ void operator()(const pg8::f32x4 (&acc)[2][2][4][2], const pg8::Unit& u, int wr, int wc, int fr, int fq) const {
; #pragma unroll
;         for (int ai = 0; ai < 2; ++ai)
; #pragma unroll
;             for (int m = 0; m < 4; ++m) { float* rowp = part + (size_t)(ai * 128 + wr * 64 + m * 16 + fr) * 256 + wc * 32 + 8 * fq;
; #pragma unroll
;                 for (int bj = 0; bj < 2; ++bj) { *(f32x4*)(rowp + bj * 128) = acc[ai][bj][m][0]; *(f32x4*)(rowp + bj * 128 + 4) = acc[ai][bj][m][1]; } }
;     }
.LBB0_2149:
	s_add_u32 s0, s28, 0x25e00000
	s_addc_u32 s1, s29, 0
	s_ashr_i32 s3, s2, 31
	s_lshl_b64 s[4:5], s[2:3], 18
	v_mov_b32_e32 v131, 0
	s_add_u32 s4, s0, s4
	v_add_u32_e32 v130, 0xb0, v138
	v_add_u32_e32 v134, 0xa0, v138
	v_mov_b32_e32 v135, v131
	v_add_u32_e32 v136, 0x90, v138
	v_mov_b32_e32 v137, v131
	v_add_u32_e32 v140, 0x80, v138
	v_mov_b32_e32 v141, v131
	v_or_b32_e32 v142, 48, v138
	v_mov_b32_e32 v143, v131
	v_or_b32_e32 v144, 32, v138
	v_mov_b32_e32 v145, v131
	v_or_b32_e32 v146, 16, v138
	v_mov_b32_e32 v147, v131
	v_mov_b32_e32 v139, v131
	s_addc_u32 s5, s1, s5
	v_lshlrev_b64 v[132:133], 10, v[130:131]
	v_lshlrev_b64 v[134:135], 10, v[134:135]
	v_lshlrev_b64 v[136:137], 10, v[136:137]
	v_lshlrev_b64 v[140:141], 10, v[140:141]
	v_lshlrev_b64 v[142:143], 10, v[142:143]
	v_lshlrev_b64 v[144:145], 10, v[144:145]
	v_lshlrev_b64 v[146:147], 10, v[146:147]
	v_lshlrev_b64 v[138:139], 10, v[138:139]
	s_mov_b32 s7, 0
	v_lshl_add_u64 v[132:133], s[4:5], 0, v[132:133]
	s_lshl_b32 s6, s20, 2
	v_lshl_add_u64 v[134:135], s[4:5], 0, v[134:135]
	v_lshl_add_u64 v[136:137], s[4:5], 0, v[136:137]
	v_lshl_add_u64 v[140:141], s[4:5], 0, v[140:141]
	v_lshl_add_u64 v[142:143], s[4:5], 0, v[142:143]
	v_lshl_add_u64 v[144:145], s[4:5], 0, v[144:145]
	v_lshl_add_u64 v[146:147], s[4:5], 0, v[146:147]
	v_lshl_add_u64 v[138:139], s[4:5], 0, v[138:139]
	v_lshl_add_u64 v[132:133], v[132:133], 0, s[6:7]
	v_lshlrev_b32_e32 v130, 2, v156
	v_lshl_add_u64 v[134:135], v[134:135], 0, s[6:7]
	v_lshl_add_u64 v[136:137], v[136:137], 0, s[6:7]
	v_lshl_add_u64 v[140:141], v[140:141], 0, s[6:7]
	v_lshl_add_u64 v[142:143], v[142:143], 0, s[6:7]
	v_lshl_add_u64 v[144:145], v[144:145], 0, s[6:7]
	v_lshl_add_u64 v[146:147], v[146:147], 0, s[6:7]
	v_lshl_add_u64 v[138:139], v[138:139], 0, s[6:7]
	v_lshl_add_u64 v[132:133], v[132:133], 0, v[130:131]
	v_lshl_add_u64 v[134:135], v[134:135], 0, v[130:131]
	v_lshl_add_u64 v[136:137], v[136:137], 0, v[130:131]
	v_lshl_add_u64 v[140:141], v[140:141], 0, v[130:131]
	v_lshl_add_u64 v[142:143], v[142:143], 0, v[130:131]
	v_lshl_add_u64 v[144:145], v[144:145], 0, v[130:131]
	v_lshl_add_u64 v[146:147], v[146:147], 0, v[130:131]
	v_lshl_add_u64 v[130:131], v[138:139], 0, v[130:131]
	global_store_dwordx4 v[130:131], v[126:129], off
	global_store_dwordx4 v[130:131], v[122:125], off offset:16
	global_store_dwordx4 v[130:131], v[102:105], off offset:512
	global_store_dwordx4 v[130:131], v[94:97], off offset:528
	global_store_dwordx4 v[146:147], v[118:121], off
	global_store_dwordx4 v[146:147], v[114:117], off offset:16
	global_store_dwordx4 v[146:147], v[86:89], off offset:512
	global_store_dwordx4 v[146:147], v[82:85], off offset:528
	global_store_dwordx4 v[144:145], v[110:113], off
	global_store_dwordx4 v[144:145], v[106:109], off offset:16
	global_store_dwordx4 v[144:145], v[78:81], off offset:512
	global_store_dwordx4 v[144:145], v[74:77], off offset:528
	global_store_dwordx4 v[142:143], v[98:101], off
	global_store_dwordx4 v[142:143], v[90:93], off offset:16
	global_store_dwordx4 v[142:143], v[70:73], off offset:512
	global_store_dwordx4 v[142:143], v[66:69], off offset:528
	global_store_dwordx4 v[140:141], v[62:65], off
	global_store_dwordx4 v[140:141], v[58:61], off offset:16
	global_store_dwordx4 v[140:141], v[38:41], off offset:512
	global_store_dwordx4 v[140:141], v[30:33], off offset:528
	global_store_dwordx4 v[136:137], v[54:57], off
	global_store_dwordx4 v[136:137], v[50:53], off offset:16
	global_store_dwordx4 v[136:137], v[22:25], off offset:512
	global_store_dwordx4 v[136:137], v[18:21], off offset:528
	global_store_dwordx4 v[134:135], v[46:49], off
	global_store_dwordx4 v[134:135], v[42:45], off offset:16
	global_store_dwordx4 v[134:135], v[14:17], off offset:512
	global_store_dwordx4 v[134:135], v[10:13], off offset:528
	global_store_dwordx4 v[132:133], v[34:37], off
	global_store_dwordx4 v[132:133], v[26:29], off offset:16
	global_store_dwordx4 v[132:133], v[6:9], off offset:512
	global_store_dwordx4 v[132:133], v[2:5], off offset:528
	s_waitcnt vmcnt(0)
	s_barrier
	v_writelane_b32 v253, s0, 8
	v_writelane_b32 v253, s1, 9
	v_writelane_b32 v253, s3, 10
	v_writelane_b32 v253, s18, 11
	v_writelane_b32 v253, s19, 12
	v_writelane_b32 v253, s20, 13
	v_writelane_b32 v253, s21, 14
	v_writelane_b32 v253, s23, 15
	v_lshrrev_b32_e32 v168, 3, v0
	v_lshlrev_b32_e32 v169, 4, v0
	v_bfe_u32 v171, v0, 4, 2
	v_bfe_u32 v2, v0, 3, 25
	v_bfe_u32 v175, v0, 2, 4
	v_bfe_u32 v179, v0, 2, 2
	v_and_b32_e32 v182, 32, v0
	v_and_b32_e32 v172, 64, v0
	v_lshrrev_b32_e32 v180, 1, v0
	v_lshrrev_b32_e32 v181, 5, v0
	v_or_b32_e32 v178, 64, v2
	v_and_b32_e32 v170, 15, v0
	v_lshlrev_b32_e32 v173, 3, v171
	v_lshlrev_b32_e32 v174, 4, v171
	v_lshlrev_b32_e32 v176, 6, v0
	v_lshlrev_b32_e32 v177, 2, v0
	s_add_u32 s12, s28, 0x1f500000
	s_addc_u32 s13, s29, 0
	v_bitop3_b32 v159, v169, v182, 48 bitop3:0x6c
	v_or_b32_e32 v2, v159, v172
	v_and_b32_e32 v156, 24, v180
	v_and_b32_e32 v3, 4, v181
	v_and_or_b32 v4, v168, 48, v175
	v_lshrrev_b32_e32 v2, 1, v2
	v_or3_b32 v3, v3, v179, v156
	v_mul_u32_u24_e32 v160, 0xb00, v4
	v_and_or_b32 v5, v168, 32, v3
	v_or_b32_e32 v4, v2, v160
	s_add_u32 s3, s28, 0x3000000
	v_lshlrev_b32_e32 v130, 1, v4
	v_mul_u32_u24_e32 v4, 0xb00, v5
	s_addc_u32 s35, s29, 0
	v_or_b32_e32 v4, v4, v2
	s_movk_i32 s0, 0x70
	s_add_u32 s8, s28, 0x9a00000
	v_lshlrev_b32_e32 v132, 1, v4
	v_and_or_b32 v4, v178, s0, v175
	s_movk_i32 s0, 0x60
	s_addc_u32 s9, s29, 0
	v_and_or_b32 v3, v178, s0, v3
	s_add_u32 s10, s28, 0x90000
	v_mul_u32_u24_e32 v161, 0xb00, v4
	v_mul_u32_u24_e32 v3, 0xb00, v3
	s_addc_u32 s11, s29, 0
	v_or_b32_e32 v4, v161, v2
	v_or_b32_e32 v2, v3, v2
	v_and_b32_e32 v158, 0x3c0, v176
	v_and_b32_e32 v157, 32, v177
	v_lshlrev_b32_e32 v134, 1, v4
	v_lshlrev_b32_e32 v136, 1, v2
	v_bitop3_b32 v162, v174, v157, v158 bitop3:0x36
	v_readfirstlane_b32 s6, v0
	s_nop 4
	s_branch .Lp13_r1
.Lp13_post:
	s_waitcnt vmcnt(0)
	v_cmp_eq_u32_e32 vcc, 0, v0
	s_waitcnt vmcnt(0)
	s_barrier
	s_and_saveexec_b64 s[4:5], vcc
	s_cbranch_execz .LBB0_2202
	v_mov_b32_e32 v2, s97
	s_waitcnt vmcnt(0) expcnt(0) lgkmcnt(0)
	ds_read_b32 v4, v2
	ds_read_b32 v2, v2 offset:4
	s_waitcnt lgkmcnt(1)
	v_cmp_ne_u32_e32 vcc, 0, v4
	s_cbranch_vccnz .LBB0_2170
	v_readlane_b32 s8, v252, 8
	v_readlane_b32 s9, v252, 9
	s_load_dwordx2 s[6:7], s[8:9], 0x4
	s_mov_b32 s22, 1
	v_mov_b32_e32 v18, 0
	s_waitcnt lgkmcnt(0)
	s_mul_i32 s6, s6, s7
	s_lshl_b32 s23, s6, 8
	s_add_u32 s6, s28, 0x1000
	s_addc_u32 s7, s29, 0
	s_add_u32 s8, s28, 0x1100
	s_addc_u32 s9, s29, 0
	s_add_u32 s10, s28, 0x1200
	s_addc_u32 s11, s29, 0
	s_add_u32 s12, s28, 0x1300
	s_addc_u32 s13, s29, 0
	s_branch .LBB0_2153

; __global__ void __launch_bounds__(512, 2) fwd(Args a) {
	.amdhsa_kernel _Z3fwd4Args
		.amdhsa_group_segment_fixed_size 0
		.amdhsa_private_segment_fixed_size 0
		.amdhsa_kernarg_size 432
		.amdhsa_user_sgpr_count 2
		.amdhsa_user_sgpr_dispatch_ptr 0
		.amdhsa_user_sgpr_queue_ptr 0
		.amdhsa_user_sgpr_kernarg_segment_ptr 1
		.amdhsa_user_sgpr_dispatch_id 0
		.amdhsa_user_sgpr_kernarg_preload_length 0
		.amdhsa_user_sgpr_kernarg_preload_offset 0
		.amdhsa_user_sgpr_private_segment_size 0
		.amdhsa_uses_dynamic_stack 0
		.amdhsa_enable_private_segment 0
		.amdhsa_system_sgpr_workgroup_id_x 1
		.amdhsa_system_sgpr_workgroup_id_y 0
		.amdhsa_system_sgpr_workgroup_id_z 0
		.amdhsa_system_sgpr_workgroup_info 0
		.amdhsa_system_vgpr_workitem_id 0
		.amdhsa_next_free_vgpr 256
		.amdhsa_next_free_sgpr 102
		.amdhsa_accum_offset 256
		.amdhsa_reserve_vcc 1
		.amdhsa_float_round_mode_32 0
		.amdhsa_float_round_mode_16_64 0
		.amdhsa_float_denorm_mode_32 3
		.amdhsa_float_denorm_mode_16_64 3
		.amdhsa_dx10_clamp 1
		.amdhsa_ieee_mode 1
		.amdhsa_fp16_overflow 0
		.amdhsa_tg_split 0
		.amdhsa_exception_fp_ieee_invalid_op 0
		.amdhsa_exception_fp_denorm_src 0
		.amdhsa_exception_fp_ieee_div_zero 0
		.amdhsa_exception_fp_ieee_overflow 0
		.amdhsa_exception_fp_ieee_underflow 0
		.amdhsa_exception_fp_ieee_inexact 0
		.amdhsa_exception_int_div_zero 0
	.end_amdhsa_kernel

; __global__ void __launch_bounds__(512, 2) fwd(Args a) {
amdhsa.kernels:
  - .agpr_count:     0
    .args:
      - .offset:         0
        .size:           176
        .value_kind:     by_value
      - .offset:         176
        .size:           4
        .value_kind:     hidden_block_count_x
      - .offset:         180
        .size:           4
        .value_kind:     hidden_block_count_y
      - .offset:         184
        .size:           4
        .value_kind:     hidden_block_count_z
      - .offset:         188
        .size:           2
        .value_kind:     hidden_group_size_x
      - .offset:         190
        .size:           2
        .value_kind:     hidden_group_size_y
      - .offset:         192
        .size:           2
        .value_kind:     hidden_group_size_z
      - .offset:         194
        .size:           2
        .value_kind:     hidden_remainder_x
      - .offset:         196
        .size:           2
        .value_kind:     hidden_remainder_y
      - .offset:         198
        .size:           2
        .value_kind:     hidden_remainder_z
      - .offset:         216
        .size:           8
        .value_kind:     hidden_global_offset_x
      - .offset:         224
        .size:           8
        .value_kind:     hidden_global_offset_y
      - .offset:         232
        .size:           8
        .value_kind:     hidden_global_offset_z
      - .offset:         240
        .size:           2
        .value_kind:     hidden_grid_dims
      - .offset:         296
        .size:           4
        .value_kind:     hidden_dynamic_lds_size
    .group_segment_fixed_size: 0
    .kernarg_segment_align: 8
    .kernarg_segment_size: 432
    .language:       OpenCL C
    .language_version:
      - 2
      - 0
    .max_flat_workgroup_size: 512
    .name:           _Z3fwd4Args
    .private_segment_fixed_size: 0
    .sgpr_count:     108
    .sgpr_spill_count: 20
    .symbol:         _Z3fwd4Args.kd
    .uniform_work_group_size: 1
    .uses_dynamic_stack: false
    .vgpr_count:     256
    .vgpr_spill_count: 0
    .wavefront_size: 64
